# slot pass parameters (first workgroup, wave count) derived from gridDim instead of constants; same work split as the phase-1 slot version
# baseline (speedup 1.0000x reference)
; #define LAS __attribute__((address_space(3)))
; DI int ltid(int wv) { asm volatile("" : "+s"(wv)); int l = __builtin_amdgcn_mbcnt_hi(~0u, __builtin_amdgcn_mbcnt_lo(~0u, 0u)); asm volatile("" : "+v"(l)); return wv * 64 + l; }
; DI void phase_prologue(int wv, const ArgP a, LAS unsigned char* lds, int parts) {
;     unsigned char* ws = a.ws();
;     const int tid = ltid(wv), wave = tid >> 6, lane = tid & 63;
;     LAS float* scr = (LAS float*)(lds + wave * 8448);
;     const int gw = blockIdx.x * 8 + wave, NGW = gridDim.x * 8; int cum = 0;
;     if (parts & 1) {
;     { FW1 f{a.in(3), a.in(2)}; tr_items(f, 1024, 1536, (bf16_t*)(ws + O_W1T), scr, gw, NGW, lane, cum); }
.Lpro_entry:
	s_cmp_eq_u32 s90, 0
	s_cselect_b64 s[94:95], -1, 0
	s_cselect_b64 s[96:97], 0, -1
	v_mbcnt_lo_u32_b32 v0, -1, 0
	s_lshr_b32 s50, s48, 6
	v_mbcnt_hi_u32_b32 v192, -1, v0
	s_mov_b64 s[2:3], s[82:83]
	s_mov_b32 s0, s50
	v_mov_b32_e32 v14, v192
	s_load_dwordx2 s[12:13], s[2:3], 0xe8
	s_load_dword s24, s[82:83], 0xf8
	s_lshl_b32 s46, s80, 3
	s_sub_i32 s46, s46, s91
	s_add_u32 s88, s82, 0xf8
	s_addc_u32 s89, s83, 0
	v_lshl_add_u32 v15, s0, 6, v14
	s_waitcnt lgkmcnt(0)
	s_lshl_b32 s14, s24, 3
	s_cmp_eq_u32 s90, 1
	s_cselect_b32 s14, s93, s14
	s_abs_i32 s15, s14
	v_cvt_f32_u32_e32 v1, s15
	v_ashrrev_i32_e32 v0, 6, v15
	s_movk_i32 s0, 0x2100
	v_mul_lo_u32 v2, v0, s0
	v_rcp_iflag_f32_e32 v3, v1
	v_add_u32_e32 v20, 0, v2
	s_sub_i32 s0, 0, s15
	v_add_u32_e32 v0, s46, v0
	v_mul_f32_e32 v2, 0x4f7ffffe, v3
	v_cvt_u32_f32_e32 v2, v2
	v_sub_u32_e32 v3, 0, v0
	v_max_i32_e32 v3, v0, v3
	v_ashrrev_i32_e32 v1, 31, v0
	v_readfirstlane_b32 s25, v2
	s_mul_i32 s0, s0, s25
	s_mul_hi_u32 s0, s25, s0
	s_add_i32 s25, s25, s0
	v_mul_hi_u32 v2, v3, s25
	v_mul_lo_u32 v2, v2, s15
	v_sub_u32_e32 v2, v3, v2
	v_subrev_u32_e32 v3, s15, v2
	v_cmp_le_u32_e32 vcc, s15, v2
	v_and_b32_e32 v16, 63, v14
	s_movk_i32 s0, 0x300
	v_cndmask_b32_e32 v2, v2, v3, vcc
	v_subrev_u32_e32 v3, s15, v2
	v_cmp_le_u32_e32 vcc, s15, v2
	s_mul_hi_u32 s16, s25, 0x300
	v_and_b32_e32 v18, 31, v14
	v_cndmask_b32_e32 v2, v2, v3, vcc
	v_xor_b32_e32 v2, v2, v1
	v_sub_u32_e32 v2, v2, v1
	v_ashrrev_i32_e32 v3, 31, v2
	v_and_b32_e32 v3, s14, v3
	v_add_u32_e32 v10, v3, v2
	v_cmp_gt_i32_e32 vcc, s0, v10
	v_lshrrev_b32_e32 v17, 5, v16
	v_lshrrev_b32_e32 v19, 3, v16
	v_lshlrev_b32_e32 v21, 3, v16
	s_and_b64 vcc, vcc, s[94:95]
	s_and_saveexec_b64 s[0:1], vcc
	s_cbranch_execz .LBB0_82
	s_load_dwordx4 s[4:7], s[2:3], 0x10
	v_lshrrev_b32_e32 v13, 3, v16
	v_and_b32_e32 v2, 56, v21
	v_and_b32_e32 v11, 31, v14
	v_lshrrev_b32_e32 v12, 5, v16
	v_mul_u32_u24_e32 v5, 0x84, v2
	v_lshlrev_b32_e32 v2, 1, v2
	v_mov_b32_e32 v3, 0
	v_lshlrev_b32_e32 v6, 2, v13
	v_lshl_add_u32 v4, v11, 2, v20
	v_lshl_add_u64 v[2:3], s[12:13], 0, v[2:3]
	s_mov_b64 s[8:9], 0x3e0b000
	v_add3_u32 v22, v20, v5, v6
	v_mul_u32_u24_e32 v5, 0x84, v12
	v_lshl_add_u64 v[2:3], v[2:3], 0, s[8:9]
	v_lshlrev_b32_e32 v23, 5, v10
	s_lshl_b32 s17, s14, 5
	s_mov_b64 s[8:9], 0
	s_mov_b32 s18, 0x2aaaaaab
	s_movk_i32 s19, 0xfa00
	s_movk_i32 s20, 0x5a0
	s_movk_i32 s21, 0x1680
	v_add_u32_e32 v24, v4, v5
	s_movk_i32 s22, 0x2ff
	s_branch .LBB0_18

; #define WSB (getargs().ws())
; #define GSYNC() xcd_barrier(wv, BARW, BARST)
; __global__ void __launch_bounds__(512, 2) fwd_kernel(Args a_unused) {
;     ...
;       pg8::gemm_phase<false>(wv, lds, XBP, 1024, (const bf16_t*)(WSB + O_W1T), 1024, 1024, 64, 6, E); }
;     }
;     ...
;     GSYNC();
.LBB0_388:
	s_load_dword s91, s[88:89], 0x0
	s_movk_i32 s92, 0x180
	s_waitcnt lgkmcnt(0)
.Lslot_mod:
	s_cmp_ge_u32 s92, s91
	s_cbranch_scc0 .Lslot_mod_done
	s_sub_u32 s92, s92, s91
	s_branch .Lslot_mod
.Lslot_mod_done:
	s_cmp_lt_u32 s80, s92
	s_cbranch_scc1 .Lslot_skip
	s_sub_u32 s93, s91, s92
	s_lshl_b32 s93, s93, 3
	s_lshl_b32 s91, s92, 3
	s_barrier
	s_mov_b32 s90, 1
	s_branch .Lpro_entry
